# in-proj epilogue no longer waits for store completion between row groups; sample-row gated-merge split-K loads of branches 0 and 1 requested together
# baseline (speedup 1.0000x reference)
; __device__ __forceinline__ unsigned cvt_pk_bf16(float lo, float hi) { const f32x2 v = {lo, hi}; const bf16x2_t b = __builtin_convertvector(v, bf16x2_t); return __builtin_bit_cast(unsigned, b); }
; __device__ __forceinline__ float sigmoidf_(float x) { return __builtin_amdgcn_rcpf(1.0f + __expf(-x)); }
; __device__ __forceinline__ float siluf_(float x) { return x * sigmoidf_(x); }
;     __device__ __forceinline__ void operator()(const AccT& acc, const Unit& u, int wr, int wc, int fr, int fq) const {
;     ...
;                 const int row = u.pm * 256 + ai * 128 + wr * 64 + m * 16 + fr;
;                 bf16_t* rowp = O + (size_t)row * NIN + pn * 256 + wc * 32 + 8 * fq;
;                 f32x4 r0 = (f32x4){1.f, 0.f, 1.f, 0.f}, r1 = r0;
;                 if (mode >= 4) { const int pidx = row < NPROMPT ? (row & (SEQ - 1)) : SEQ; const f32x4* rp = (const f32x4*)(rot + ((size_t)pidx * 64 + 16 * wc + 4 * fq) * 2); r0 = rp[0]; r1 = rp[1]; }
; #pragma unroll
;                 for (int bj = 0; bj < 2; ++bj) {
;                     f32x4 v0 = acc[ai][bj][m][0], v1 = acc[ai][bj][m][1];
;                     if (mode >= 4) {
;                         f32x4 a, b;
;                         a[0] = v0[0] * r0[0] - v0[1] * r0[1]; a[1] = v0[1] * r0[0] + v0[0] * r0[1];
;                         a[2] = v0[2] * r0[2] - v0[3] * r0[3]; a[3] = v0[3] * r0[2] + v0[2] * r0[3];
;                         b[0] = v1[0] * r1[0] - v1[1] * r1[1]; b[1] = v1[1] * r1[0] + v1[0] * r1[1];
;                         b[2] = v1[2] * r1[2] - v1[3] * r1[3]; b[3] = v1[3] * r1[2] + v1[2] * r1[3];
;                         v0 = a; v1 = b;
;                         if (mode == 5) { v0 *= SC; v1 *= SC; }
;                     } else if (mode == 1) { v0 *= SC; v1 *= SC; }
;                     else if (mode == 2) {
; #pragma unroll
;                         for (int j = 0; j < 4; ++j) { v0[j] = siluf_(v0[j]); v1[j] = siluf_(v1[j]); } }
;                     else if (mode == 3) {
; #pragma unroll
;                         for (int j = 0; j < 4; ++j) { v0[j] = sigmoidf_(v0[j]); v1[j] = sigmoidf_(v1[j]); } }
;                     u32x4 w; w.x = cvt_pk_bf16(v0[0], v0[1]); w.y = cvt_pk_bf16(v0[2], v0[3]); w.z = cvt_pk_bf16(v1[0], v1[1]); w.w = cvt_pk_bf16(v1[2], v1[3]);
;                     *(u32x4*)(rowp + bj * 128) = w;
.LBB0_281:
	v_cvt_pk_bf16_f32 v114, v124, v125
	v_cvt_pk_bf16_f32 v115, v128, v129
	v_cvt_pk_bf16_f32 v116, v126, v127
	v_cvt_pk_bf16_f32 v117, v168, v169
	global_store_dwordx4 v[122:123], v[114:117], off offset:256
	s_andn2_b64 vcc, exec, s[30:31]
	s_nop 1
	v_or_b32_e32 v130, 16, v196
	v_cndmask_b32_e64 v114, 0, 1, s[30:31]
	v_cmp_ne_u32_e64 s[10:11], 1, v114
	s_cbranch_vccnz .LBB0_283
	v_lshlrev_b32_e32 v114, 7, v130
	v_and_b32_e32 v114, 0x3ef80, v114
	v_cmp_gt_i32_e32 vcc, s39, v130
	s_nop 1
	v_cndmask_b32_e32 v114, v185, v114, vcc
	v_or_b32_e32 v114, v114, v194
	v_lshlrev_b32_e32 v114, 2, v114
	global_load_dwordx4 v[118:121], v114, s[12:13]
	s_nop 0
	global_load_dwordx4 v[114:117], v114, s[12:13] offset:16
	s_and_b64 vcc, exec, s[8:9]
	s_mov_b64 s[30:31], -1
	s_cbranch_vccnz .LBB0_295
	s_branch .LBB0_284

; __device__ __forceinline__ unsigned cvt_pk_bf16(float lo, float hi) { const f32x2 v = {lo, hi}; const bf16x2_t b = __builtin_convertvector(v, bf16x2_t); return __builtin_bit_cast(unsigned, b); }
; __device__ __forceinline__ float sigmoidf_(float x) { return __builtin_amdgcn_rcpf(1.0f + __expf(-x)); }
; __device__ __forceinline__ float siluf_(float x) { return x * sigmoidf_(x); }
;     __device__ __forceinline__ void operator()(const AccT& acc, const Unit& u, int wr, int wc, int fr, int fq) const {
;     ...
;                 const int row = u.pm * 256 + ai * 128 + wr * 64 + m * 16 + fr;
;                 bf16_t* rowp = O + (size_t)row * NIN + pn * 256 + wc * 32 + 8 * fq;
;                 f32x4 r0 = (f32x4){1.f, 0.f, 1.f, 0.f}, r1 = r0;
;                 if (mode >= 4) { const int pidx = row < NPROMPT ? (row & (SEQ - 1)) : SEQ; const f32x4* rp = (const f32x4*)(rot + ((size_t)pidx * 64 + 16 * wc + 4 * fq) * 2); r0 = rp[0]; r1 = rp[1]; }
; #pragma unroll
;                 for (int bj = 0; bj < 2; ++bj) {
;                     f32x4 v0 = acc[ai][bj][m][0], v1 = acc[ai][bj][m][1];
;                     if (mode >= 4) {
;                         f32x4 a, b;
;                         a[0] = v0[0] * r0[0] - v0[1] * r0[1]; a[1] = v0[1] * r0[0] + v0[0] * r0[1];
;                         a[2] = v0[2] * r0[2] - v0[3] * r0[3]; a[3] = v0[3] * r0[2] + v0[2] * r0[3];
;                         b[0] = v1[0] * r1[0] - v1[1] * r1[1]; b[1] = v1[1] * r1[0] + v1[0] * r1[1];
;                         b[2] = v1[2] * r1[2] - v1[3] * r1[3]; b[3] = v1[3] * r1[2] + v1[2] * r1[3];
;                         v0 = a; v1 = b;
;                         if (mode == 5) { v0 *= SC; v1 *= SC; }
;                     } else if (mode == 1) { v0 *= SC; v1 *= SC; }
;                     else if (mode == 2) {
; #pragma unroll
;                         for (int j = 0; j < 4; ++j) { v0[j] = siluf_(v0[j]); v1[j] = siluf_(v1[j]); } }
;                     else if (mode == 3) {
; #pragma unroll
;                         for (int j = 0; j < 4; ++j) { v0[j] = sigmoidf_(v0[j]); v1[j] = sigmoidf_(v1[j]); } }
;                     u32x4 w; w.x = cvt_pk_bf16(v0[0], v0[1]); w.y = cvt_pk_bf16(v0[2], v0[3]); w.z = cvt_pk_bf16(v1[0], v1[1]); w.w = cvt_pk_bf16(v1[2], v1[3]);
;                     *(u32x4*)(rowp + bj * 128) = w;
.LBB0_311:
	v_cvt_pk_bf16_f32 v98, v108, v109
	v_cvt_pk_bf16_f32 v99, v112, v113
	v_cvt_pk_bf16_f32 v100, v110, v111
	v_cvt_pk_bf16_f32 v101, v122, v123
	s_and_b64 vcc, exec, s[10:11]
	s_nop 1
	v_or_b32_e32 v114, 32, v196
	global_store_dwordx4 v[106:107], v[98:101], off offset:256
	s_cbranch_vccnz .LBB0_313
	s_nop 0
	v_lshlrev_b32_e32 v98, 7, v114
	v_and_b32_e32 v98, 0x3f780, v98
	v_cmp_gt_i32_e32 vcc, s39, v114
	s_nop 1
	v_cndmask_b32_e32 v98, v185, v98, vcc
	v_or_b32_e32 v98, v98, v194
	v_lshlrev_b32_e32 v98, 2, v98
	global_load_dwordx4 v[102:105], v98, s[12:13]
	s_nop 0
	global_load_dwordx4 v[98:101], v98, s[12:13] offset:16
	s_and_b64 vcc, exec, s[8:9]
	s_mov_b64 s[30:31], -1
	s_cbranch_vccnz .LBB0_325
	s_branch .LBB0_314

; __device__ __forceinline__ unsigned cvt_pk_bf16(float lo, float hi) { const f32x2 v = {lo, hi}; const bf16x2_t b = __builtin_convertvector(v, bf16x2_t); return __builtin_bit_cast(unsigned, b); }
; __device__ __forceinline__ float sigmoidf_(float x) { return __builtin_amdgcn_rcpf(1.0f + __expf(-x)); }
; __device__ __forceinline__ float siluf_(float x) { return x * sigmoidf_(x); }
;     __device__ __forceinline__ void operator()(const AccT& acc, const Unit& u, int wr, int wc, int fr, int fq) const {
;     ...
;                 const int row = u.pm * 256 + ai * 128 + wr * 64 + m * 16 + fr;
;                 bf16_t* rowp = O + (size_t)row * NIN + pn * 256 + wc * 32 + 8 * fq;
;                 f32x4 r0 = (f32x4){1.f, 0.f, 1.f, 0.f}, r1 = r0;
;                 if (mode >= 4) { const int pidx = row < NPROMPT ? (row & (SEQ - 1)) : SEQ; const f32x4* rp = (const f32x4*)(rot + ((size_t)pidx * 64 + 16 * wc + 4 * fq) * 2); r0 = rp[0]; r1 = rp[1]; }
; #pragma unroll
;                 for (int bj = 0; bj < 2; ++bj) {
;                     f32x4 v0 = acc[ai][bj][m][0], v1 = acc[ai][bj][m][1];
;                     if (mode >= 4) {
;                         f32x4 a, b;
;                         a[0] = v0[0] * r0[0] - v0[1] * r0[1]; a[1] = v0[1] * r0[0] + v0[0] * r0[1];
;                         a[2] = v0[2] * r0[2] - v0[3] * r0[3]; a[3] = v0[3] * r0[2] + v0[2] * r0[3];
;                         b[0] = v1[0] * r1[0] - v1[1] * r1[1]; b[1] = v1[1] * r1[0] + v1[0] * r1[1];
;                         b[2] = v1[2] * r1[2] - v1[3] * r1[3]; b[3] = v1[3] * r1[2] + v1[2] * r1[3];
;                         v0 = a; v1 = b;
;                         if (mode == 5) { v0 *= SC; v1 *= SC; }
;                     } else if (mode == 1) { v0 *= SC; v1 *= SC; }
;                     else if (mode == 2) {
; #pragma unroll
;                         for (int j = 0; j < 4; ++j) { v0[j] = siluf_(v0[j]); v1[j] = siluf_(v1[j]); } }
;                     else if (mode == 3) {
; #pragma unroll
;                         for (int j = 0; j < 4; ++j) { v0[j] = sigmoidf_(v0[j]); v1[j] = sigmoidf_(v1[j]); } }
;                     u32x4 w; w.x = cvt_pk_bf16(v0[0], v0[1]); w.y = cvt_pk_bf16(v0[2], v0[3]); w.z = cvt_pk_bf16(v1[0], v1[1]); w.w = cvt_pk_bf16(v1[2], v1[3]);
;                     *(u32x4*)(rowp + bj * 128) = w;
.LBB0_341:
	v_cvt_pk_bf16_f32 v82, v92, v93
	v_cvt_pk_bf16_f32 v83, v96, v97
	v_cvt_pk_bf16_f32 v84, v94, v95
	v_cvt_pk_bf16_f32 v85, v106, v107
	s_and_b64 vcc, exec, s[10:11]
	s_nop 1
	v_or_b32_e32 v98, 48, v196
	global_store_dwordx4 v[90:91], v[82:85], off offset:256
	s_cbranch_vccnz .LBB0_343
	s_nop 0
	v_lshlrev_b32_e32 v82, 7, v98
	v_and_b32_e32 v82, 0x3ff80, v82
	v_cmp_gt_i32_e32 vcc, s39, v98
	s_nop 1
	v_cndmask_b32_e32 v82, v185, v82, vcc
	v_or_b32_e32 v82, v82, v194
	v_lshlrev_b32_e32 v82, 2, v82
	global_load_dwordx4 v[86:89], v82, s[12:13]
	s_nop 0
	global_load_dwordx4 v[82:85], v82, s[12:13] offset:16
	s_and_b64 vcc, exec, s[8:9]
	s_mov_b64 s[30:31], -1
	s_cbranch_vccnz .LBB0_355
	s_branch .LBB0_344

; __device__ __forceinline__ unsigned cvt_pk_bf16(float lo, float hi) { const f32x2 v = {lo, hi}; const bf16x2_t b = __builtin_convertvector(v, bf16x2_t); return __builtin_bit_cast(unsigned, b); }
; __device__ __forceinline__ float sigmoidf_(float x) { return __builtin_amdgcn_rcpf(1.0f + __expf(-x)); }
; __device__ __forceinline__ float siluf_(float x) { return x * sigmoidf_(x); }
;     __device__ __forceinline__ void operator()(const AccT& acc, const Unit& u, int wr, int wc, int fr, int fq) const {
;     ...
;                 const int row = u.pm * 256 + ai * 128 + wr * 64 + m * 16 + fr;
;                 bf16_t* rowp = O + (size_t)row * NIN + pn * 256 + wc * 32 + 8 * fq;
;                 f32x4 r0 = (f32x4){1.f, 0.f, 1.f, 0.f}, r1 = r0;
;                 if (mode >= 4) { const int pidx = row < NPROMPT ? (row & (SEQ - 1)) : SEQ; const f32x4* rp = (const f32x4*)(rot + ((size_t)pidx * 64 + 16 * wc + 4 * fq) * 2); r0 = rp[0]; r1 = rp[1]; }
; #pragma unroll
;                 for (int bj = 0; bj < 2; ++bj) {
;                     f32x4 v0 = acc[ai][bj][m][0], v1 = acc[ai][bj][m][1];
;                     if (mode >= 4) {
;                         f32x4 a, b;
;                         a[0] = v0[0] * r0[0] - v0[1] * r0[1]; a[1] = v0[1] * r0[0] + v0[0] * r0[1];
;                         a[2] = v0[2] * r0[2] - v0[3] * r0[3]; a[3] = v0[3] * r0[2] + v0[2] * r0[3];
;                         b[0] = v1[0] * r1[0] - v1[1] * r1[1]; b[1] = v1[1] * r1[0] + v1[0] * r1[1];
;                         b[2] = v1[2] * r1[2] - v1[3] * r1[3]; b[3] = v1[3] * r1[2] + v1[2] * r1[3];
;                         v0 = a; v1 = b;
;                         if (mode == 5) { v0 *= SC; v1 *= SC; }
;                     } else if (mode == 1) { v0 *= SC; v1 *= SC; }
;                     else if (mode == 2) {
; #pragma unroll
;                         for (int j = 0; j < 4; ++j) { v0[j] = siluf_(v0[j]); v1[j] = siluf_(v1[j]); } }
;                     else if (mode == 3) {
; #pragma unroll
;                         for (int j = 0; j < 4; ++j) { v0[j] = sigmoidf_(v0[j]); v1[j] = sigmoidf_(v1[j]); } }
;                     u32x4 w; w.x = cvt_pk_bf16(v0[0], v0[1]); w.y = cvt_pk_bf16(v0[2], v0[3]); w.z = cvt_pk_bf16(v1[0], v1[1]); w.w = cvt_pk_bf16(v1[2], v1[3]);
;                     *(u32x4*)(rowp + bj * 128) = w;
.LBB0_371:
	v_cvt_pk_bf16_f32 v66, v76, v77
	v_cvt_pk_bf16_f32 v67, v80, v81
	v_cvt_pk_bf16_f32 v68, v78, v79
	v_cvt_pk_bf16_f32 v69, v90, v91
	s_and_b64 vcc, exec, s[10:11]
	s_nop 1
	v_add_u32_e32 v82, 0x80, v196
	global_store_dwordx4 v[74:75], v[66:69], off offset:256
	s_cbranch_vccnz .LBB0_373
	s_nop 0
	v_lshlrev_b32_e32 v66, 7, v82
	v_and_b32_e32 v66, 0x3e780, v66
	v_cmp_gt_i32_e32 vcc, s39, v82
	s_nop 1
	v_cndmask_b32_e32 v66, v185, v66, vcc
	v_or_b32_e32 v66, v66, v194
	v_lshlrev_b32_e32 v66, 2, v66
	global_load_dwordx4 v[70:73], v66, s[12:13]
	s_nop 0
	global_load_dwordx4 v[66:69], v66, s[12:13] offset:16
	s_and_b64 vcc, exec, s[8:9]
	s_mov_b64 s[30:31], -1
	s_cbranch_vccnz .LBB0_385
	s_branch .LBB0_374

; __device__ __forceinline__ unsigned cvt_pk_bf16(float lo, float hi) { const f32x2 v = {lo, hi}; const bf16x2_t b = __builtin_convertvector(v, bf16x2_t); return __builtin_bit_cast(unsigned, b); }
; __device__ __forceinline__ float sigmoidf_(float x) { return __builtin_amdgcn_rcpf(1.0f + __expf(-x)); }
; __device__ __forceinline__ float siluf_(float x) { return x * sigmoidf_(x); }
;     __device__ __forceinline__ void operator()(const AccT& acc, const Unit& u, int wr, int wc, int fr, int fq) const {
;     ...
;                 const int row = u.pm * 256 + ai * 128 + wr * 64 + m * 16 + fr;
;                 bf16_t* rowp = O + (size_t)row * NIN + pn * 256 + wc * 32 + 8 * fq;
;                 f32x4 r0 = (f32x4){1.f, 0.f, 1.f, 0.f}, r1 = r0;
;                 if (mode >= 4) { const int pidx = row < NPROMPT ? (row & (SEQ - 1)) : SEQ; const f32x4* rp = (const f32x4*)(rot + ((size_t)pidx * 64 + 16 * wc + 4 * fq) * 2); r0 = rp[0]; r1 = rp[1]; }
; #pragma unroll
;                 for (int bj = 0; bj < 2; ++bj) {
;                     f32x4 v0 = acc[ai][bj][m][0], v1 = acc[ai][bj][m][1];
;                     if (mode >= 4) {
;                         f32x4 a, b;
;                         a[0] = v0[0] * r0[0] - v0[1] * r0[1]; a[1] = v0[1] * r0[0] + v0[0] * r0[1];
;                         a[2] = v0[2] * r0[2] - v0[3] * r0[3]; a[3] = v0[3] * r0[2] + v0[2] * r0[3];
;                         b[0] = v1[0] * r1[0] - v1[1] * r1[1]; b[1] = v1[1] * r1[0] + v1[0] * r1[1];
;                         b[2] = v1[2] * r1[2] - v1[3] * r1[3]; b[3] = v1[3] * r1[2] + v1[2] * r1[3];
;                         v0 = a; v1 = b;
;                         if (mode == 5) { v0 *= SC; v1 *= SC; }
;                     } else if (mode == 1) { v0 *= SC; v1 *= SC; }
;                     else if (mode == 2) {
; #pragma unroll
;                         for (int j = 0; j < 4; ++j) { v0[j] = siluf_(v0[j]); v1[j] = siluf_(v1[j]); } }
;                     else if (mode == 3) {
; #pragma unroll
;                         for (int j = 0; j < 4; ++j) { v0[j] = sigmoidf_(v0[j]); v1[j] = sigmoidf_(v1[j]); } }
;                     u32x4 w; w.x = cvt_pk_bf16(v0[0], v0[1]); w.y = cvt_pk_bf16(v0[2], v0[3]); w.z = cvt_pk_bf16(v1[0], v1[1]); w.w = cvt_pk_bf16(v1[2], v1[3]);
;                     *(u32x4*)(rowp + bj * 128) = w;
.LBB0_401:
	v_cvt_pk_bf16_f32 v50, v60, v61
	v_cvt_pk_bf16_f32 v51, v64, v65
	v_cvt_pk_bf16_f32 v52, v62, v63
	v_cvt_pk_bf16_f32 v53, v74, v75
	s_and_b64 vcc, exec, s[10:11]
	s_nop 1
	v_add_u32_e32 v66, 0x90, v196
	global_store_dwordx4 v[58:59], v[50:53], off offset:256
	s_cbranch_vccnz .LBB0_403
	s_nop 0
	v_lshlrev_b32_e32 v50, 7, v66
	v_and_b32_e32 v50, 0x3ef80, v50
	v_cmp_gt_i32_e32 vcc, s39, v66
	s_nop 1
	v_cndmask_b32_e32 v50, v185, v50, vcc
	v_or_b32_e32 v50, v50, v194
	v_lshlrev_b32_e32 v50, 2, v50
	global_load_dwordx4 v[54:57], v50, s[12:13]
	s_nop 0
	global_load_dwordx4 v[50:53], v50, s[12:13] offset:16
	s_and_b64 vcc, exec, s[8:9]
	s_mov_b64 s[30:31], -1
	s_cbranch_vccnz .LBB0_415
	s_branch .LBB0_404

; __device__ __forceinline__ unsigned cvt_pk_bf16(float lo, float hi) { const f32x2 v = {lo, hi}; const bf16x2_t b = __builtin_convertvector(v, bf16x2_t); return __builtin_bit_cast(unsigned, b); }
; __device__ __forceinline__ float sigmoidf_(float x) { return __builtin_amdgcn_rcpf(1.0f + __expf(-x)); }
; __device__ __forceinline__ float siluf_(float x) { return x * sigmoidf_(x); }
;     __device__ __forceinline__ void operator()(const AccT& acc, const Unit& u, int wr, int wc, int fr, int fq) const {
;     ...
;                 const int row = u.pm * 256 + ai * 128 + wr * 64 + m * 16 + fr;
;                 bf16_t* rowp = O + (size_t)row * NIN + pn * 256 + wc * 32 + 8 * fq;
;                 f32x4 r0 = (f32x4){1.f, 0.f, 1.f, 0.f}, r1 = r0;
;                 if (mode >= 4) { const int pidx = row < NPROMPT ? (row & (SEQ - 1)) : SEQ; const f32x4* rp = (const f32x4*)(rot + ((size_t)pidx * 64 + 16 * wc + 4 * fq) * 2); r0 = rp[0]; r1 = rp[1]; }
; #pragma unroll
;                 for (int bj = 0; bj < 2; ++bj) {
;                     f32x4 v0 = acc[ai][bj][m][0], v1 = acc[ai][bj][m][1];
;                     if (mode >= 4) {
;                         f32x4 a, b;
;                         a[0] = v0[0] * r0[0] - v0[1] * r0[1]; a[1] = v0[1] * r0[0] + v0[0] * r0[1];
;                         a[2] = v0[2] * r0[2] - v0[3] * r0[3]; a[3] = v0[3] * r0[2] + v0[2] * r0[3];
;                         b[0] = v1[0] * r1[0] - v1[1] * r1[1]; b[1] = v1[1] * r1[0] + v1[0] * r1[1];
;                         b[2] = v1[2] * r1[2] - v1[3] * r1[3]; b[3] = v1[3] * r1[2] + v1[2] * r1[3];
;                         v0 = a; v1 = b;
;                         if (mode == 5) { v0 *= SC; v1 *= SC; }
;                     } else if (mode == 1) { v0 *= SC; v1 *= SC; }
;                     else if (mode == 2) {
; #pragma unroll
;                         for (int j = 0; j < 4; ++j) { v0[j] = siluf_(v0[j]); v1[j] = siluf_(v1[j]); } }
;                     else if (mode == 3) {
; #pragma unroll
;                         for (int j = 0; j < 4; ++j) { v0[j] = sigmoidf_(v0[j]); v1[j] = sigmoidf_(v1[j]); } }
;                     u32x4 w; w.x = cvt_pk_bf16(v0[0], v0[1]); w.y = cvt_pk_bf16(v0[2], v0[3]); w.z = cvt_pk_bf16(v1[0], v1[1]); w.w = cvt_pk_bf16(v1[2], v1[3]);
;                     *(u32x4*)(rowp + bj * 128) = w;
.LBB0_431:
	v_cvt_pk_bf16_f32 v34, v44, v45
	v_cvt_pk_bf16_f32 v35, v48, v49
	v_cvt_pk_bf16_f32 v36, v46, v47
	v_cvt_pk_bf16_f32 v37, v58, v59
	s_and_b64 vcc, exec, s[10:11]
	s_nop 1
	v_add_u32_e32 v50, 0xa0, v196
	global_store_dwordx4 v[42:43], v[34:37], off offset:256
	s_cbranch_vccnz .LBB0_433
	s_nop 0
	v_lshlrev_b32_e32 v34, 7, v50
	v_and_b32_e32 v34, 0x3f780, v34
	v_cmp_gt_i32_e32 vcc, s39, v50
	s_nop 1
	v_cndmask_b32_e32 v34, v185, v34, vcc
	v_or_b32_e32 v34, v34, v194
	v_lshlrev_b32_e32 v34, 2, v34
	global_load_dwordx4 v[38:41], v34, s[12:13]
	s_nop 0
	global_load_dwordx4 v[34:37], v34, s[12:13] offset:16
	s_and_b64 vcc, exec, s[8:9]
	s_mov_b64 s[30:31], -1
	s_cbranch_vccnz .LBB0_445
	s_branch .LBB0_434

; __device__ __forceinline__ unsigned cvt_pk_bf16(float lo, float hi) { const f32x2 v = {lo, hi}; const bf16x2_t b = __builtin_convertvector(v, bf16x2_t); return __builtin_bit_cast(unsigned, b); }
; __device__ __forceinline__ float sigmoidf_(float x) { return __builtin_amdgcn_rcpf(1.0f + __expf(-x)); }
; __device__ __forceinline__ float siluf_(float x) { return x * sigmoidf_(x); }
;     __device__ __forceinline__ void operator()(const AccT& acc, const Unit& u, int wr, int wc, int fr, int fq) const {
;     ...
;                 const int row = u.pm * 256 + ai * 128 + wr * 64 + m * 16 + fr;
;                 bf16_t* rowp = O + (size_t)row * NIN + pn * 256 + wc * 32 + 8 * fq;
;                 f32x4 r0 = (f32x4){1.f, 0.f, 1.f, 0.f}, r1 = r0;
;                 if (mode >= 4) { const int pidx = row < NPROMPT ? (row & (SEQ - 1)) : SEQ; const f32x4* rp = (const f32x4*)(rot + ((size_t)pidx * 64 + 16 * wc + 4 * fq) * 2); r0 = rp[0]; r1 = rp[1]; }
; #pragma unroll
;                 for (int bj = 0; bj < 2; ++bj) {
;                     f32x4 v0 = acc[ai][bj][m][0], v1 = acc[ai][bj][m][1];
;                     if (mode >= 4) {
;                         f32x4 a, b;
;                         a[0] = v0[0] * r0[0] - v0[1] * r0[1]; a[1] = v0[1] * r0[0] + v0[0] * r0[1];
;                         a[2] = v0[2] * r0[2] - v0[3] * r0[3]; a[3] = v0[3] * r0[2] + v0[2] * r0[3];
;                         b[0] = v1[0] * r1[0] - v1[1] * r1[1]; b[1] = v1[1] * r1[0] + v1[0] * r1[1];
;                         b[2] = v1[2] * r1[2] - v1[3] * r1[3]; b[3] = v1[3] * r1[2] + v1[2] * r1[3];
;                         v0 = a; v1 = b;
;                         if (mode == 5) { v0 *= SC; v1 *= SC; }
;                     } else if (mode == 1) { v0 *= SC; v1 *= SC; }
;                     else if (mode == 2) {
; #pragma unroll
;                         for (int j = 0; j < 4; ++j) { v0[j] = siluf_(v0[j]); v1[j] = siluf_(v1[j]); } }
;                     else if (mode == 3) {
; #pragma unroll
;                         for (int j = 0; j < 4; ++j) { v0[j] = sigmoidf_(v0[j]); v1[j] = sigmoidf_(v1[j]); } }
;                     u32x4 w; w.x = cvt_pk_bf16(v0[0], v0[1]); w.y = cvt_pk_bf16(v0[2], v0[3]); w.z = cvt_pk_bf16(v1[0], v1[1]); w.w = cvt_pk_bf16(v1[2], v1[3]);
;                     *(u32x4*)(rowp + bj * 128) = w;
.LBB0_461:
	v_cvt_pk_bf16_f32 v18, v28, v29
	v_cvt_pk_bf16_f32 v19, v32, v33
	v_cvt_pk_bf16_f32 v20, v30, v31
	v_cvt_pk_bf16_f32 v21, v42, v43
	s_and_b64 vcc, exec, s[10:11]
	s_nop 1
	v_add_u32_e32 v34, 0xb0, v196
	global_store_dwordx4 v[26:27], v[18:21], off offset:256
	s_cbranch_vccnz .LBB0_463
	s_nop 0
	v_lshlrev_b32_e32 v18, 7, v34
	v_and_b32_e32 v18, 0x3ff80, v18
	v_cmp_gt_i32_e32 vcc, s39, v34
	s_nop 1
	v_cndmask_b32_e32 v18, v185, v18, vcc
	v_or_b32_e32 v18, v18, v194
	v_lshlrev_b32_e32 v18, 2, v18
	global_load_dwordx4 v[22:25], v18, s[12:13]
	s_nop 0
	global_load_dwordx4 v[18:21], v18, s[12:13] offset:16
	s_and_b64 vcc, exec, s[8:9]
	s_mov_b64 s[10:11], -1
	s_cbranch_vccnz .LBB0_475
	s_branch .LBB0_464

; #define LAS __attribute__((address_space(3)))
; __device__ __forceinline__ int fresh_bid() { int t = blockIdx.x; asm volatile("" : "+s"(t)); return t; }
; __device__ __forceinline__ void skinny_merge(ParamsK p, int l, LAS unsigned char* lds) {
;     ...
;     for (int piece = fresh_bid(); piece < 256; piece += gridDim.x) {
;         const int rh = piece & 1, cg = piece >> 1;
; #pragma unroll
;         for (int z = 0; z < 3; ++z) {
;             const bf16_t* A = (const bf16_t*)(p->ws + (z == 0 ? WS_AS5 : (z == 1 ? WS_AGLA : WS_ARET)));
;             const bf16_t* Wt = (const bf16_t*)(p->ws + (z == 0 ? WS_WS5O : (z == 1 ? WS_WGLAO : WS_WRETO)) + l * SZ_WBR);
;             const bf16_t* ap = A + (size_t)(NPROMPT + rh * 64 + r) * 1024 + q * 8 + w * 128;
;             const bf16_t* bp = Wt + (size_t)(cg * 16 + r) * 1024 + q * 8 + w * 128;
;             f32x4 acc[4];
; #pragma unroll
;             for (int mt = 0; mt < 4; ++mt) acc[mt] = (f32x4){0.f, 0.f, 0.f, 0.f};
; #pragma unroll
;             for (int ks = 0; ks < 4; ++ks) {
;                 const bf16x8 b = *(const bf16x8*)(bp + ks * 32);
; #pragma unroll
;                 for (int mt = 0; mt < 4; ++mt) { const bf16x8 a = *(const bf16x8*)(ap + (size_t)mt * 16 * 1024 + ks * 32); acc[mt] = __builtin_amdgcn_mfma_f32_16x16x32_bf16(a, b, acc[mt], 0, 0, 0); }
;             }
; #pragma unroll
;             for (int mt = 0; mt < 4; ++mt) *(LAS f32x4*)(red + (z * 8 + w) * 1024 + (mt * 64 + lane) * 4) = acc[mt];
;         }
.LBB0_1271:
	s_and_b32 s10, s8, 1
	v_lshl_or_b32 v0, s10, 17, v73
	s_and_b32 s11, s9, -16
	v_lshl_add_u64 v[2:3], s[0:1], 0, v[0:1]
	v_or_b32_e32 v4, s11, v46
	v_mov_b32_e32 v27, v1
	v_ashrrev_i32_e32 v5, 31, v4
	v_lshl_add_u64 v[2:3], v[2:3], 0, v[26:27]
	v_lshlrev_b64 v[4:5], 11, v[4:5]
	v_lshl_add_u64 v[2:3], v[22:23], 1, v[2:3]
	s_mov_b64 s[12:13], 0x290a0000
	v_lshl_add_u64 v[4:5], v[24:25], 0, v[4:5]
	v_lshl_add_u64 v[36:37], v[2:3], 0, s[12:13]
	s_mov_b32 s12, 0x7600000
	v_add_co_u32_e32 v38, vcc, s12, v4
	s_mov_b32 s12, 0x290a0000
	s_nop 0
	v_addc_co_u32_e32 v39, vcc, 0, v5, vcc
	v_add_co_u32_e32 v10, vcc, s12, v2
	s_mov_b32 s12, 0x290a8000
	s_nop 0
	v_addc_co_u32_e32 v11, vcc, 0, v3, vcc
	v_add_co_u32_e32 v40, vcc, s12, v2
	s_mov_b32 s12, 0x290b0000
	s_nop 0
	v_addc_co_u32_e32 v41, vcc, 0, v3, vcc
	v_add_co_u32_e32 v42, vcc, s12, v2
	s_mov_b32 s12, 0x290b8000
	s_nop 0
	v_addc_co_u32_e32 v43, vcc, 0, v3, vcc
	v_add_co_u32_e32 v44, vcc, s12, v2
	global_load_dwordx4 v[6:9], v[38:39], off
	s_nop 0
	v_addc_co_u32_e32 v45, vcc, 0, v3, vcc
	global_load_dwordx4 v[10:13], v[10:11], off
	s_mov_b64 s[12:13], 0x2a120000
	global_load_dwordx4 v[14:17], v[40:41], off
	global_load_dwordx4 v[18:21], v[42:43], off
	global_load_dwordx4 v[28:31], v[44:45], off
	global_load_dwordx4 v[76:79], v[38:39], off offset:64
	global_load_dwordx4 v[80:83], v[36:37], off offset:64
	global_load_dwordx4 v[84:87], v[40:41], off offset:64
	global_load_dwordx4 v[88:91], v[42:43], off offset:64
	global_load_dwordx4 v[92:95], v[44:45], off offset:64
	global_load_dwordx4 v[96:99], v[38:39], off offset:128
	global_load_dwordx4 v[100:103], v[36:37], off offset:128
	global_load_dwordx4 v[104:107], v[40:41], off offset:128
	global_load_dwordx4 v[108:111], v[42:43], off offset:128
	global_load_dwordx4 v[112:115], v[44:45], off offset:128
	global_load_dwordx4 v[116:119], v[38:39], off offset:192
	global_load_dwordx4 v[120:123], v[36:37], off offset:192
	global_load_dwordx4 v[124:127], v[40:41], off offset:192
	global_load_dwordx4 v[128:131], v[42:43], off offset:192
	global_load_dwordx4 v[132:135], v[44:45], off offset:192
	v_lshl_or_b32 v0, s10, 6, v53
	s_add_i32 s8, s8, s74
	s_add_i32 s9, s9, s97
	s_cmpk_lt_i32 s8, 0x100
	s_waitcnt vmcnt(18)
	v_mfma_f32_16x16x32_bf16 v[10:13], v[10:13], v[6:9], 0
	s_waitcnt vmcnt(17)
	v_mfma_f32_16x16x32_bf16 v[14:17], v[14:17], v[6:9], 0
	s_waitcnt vmcnt(16)
	v_mfma_f32_16x16x32_bf16 v[18:21], v[18:21], v[6:9], 0
	s_waitcnt vmcnt(15)
	v_mfma_f32_16x16x32_bf16 v[6:9], v[28:31], v[6:9], 0
	s_waitcnt vmcnt(0)
	v_mfma_f32_16x16x32_bf16 v[10:13], v[80:83], v[76:79], v[10:13]
	v_mfma_f32_16x16x32_bf16 v[14:17], v[84:87], v[76:79], v[14:17]
	v_mfma_f32_16x16x32_bf16 v[18:21], v[88:91], v[76:79], v[18:21]
	v_mfma_f32_16x16x32_bf16 v[6:9], v[92:95], v[76:79], v[6:9]
	v_mfma_f32_16x16x32_bf16 v[10:13], v[100:103], v[96:99], v[10:13]
	v_mfma_f32_16x16x32_bf16 v[14:17], v[104:107], v[96:99], v[14:17]
	v_mfma_f32_16x16x32_bf16 v[18:21], v[108:111], v[96:99], v[18:21]
	v_mfma_f32_16x16x32_bf16 v[6:9], v[112:115], v[96:99], v[6:9]
	v_mfma_f32_16x16x32_bf16 v[10:13], v[120:123], v[116:119], v[10:13]
	v_mfma_f32_16x16x32_bf16 v[14:17], v[124:127], v[116:119], v[14:17]
	v_mfma_f32_16x16x32_bf16 v[18:21], v[128:131], v[116:119], v[18:21]
	v_mfma_f32_16x16x32_bf16 v[6:9], v[132:135], v[116:119], v[6:9]
	s_nop 7
	ds_write_b128 v47, v[10:13]
	s_nop 0
	ds_write_b128 v47, v[14:17] offset:1024
	s_nop 1
	ds_write_b128 v47, v[18:21] offset:2048
	s_nop 1
	ds_write_b128 v47, v[6:9] offset:3072
	v_add_co_u32_e32 v20, vcc, s14, v4
	v_lshl_add_u64 v[6:7], v[2:3], 0, s[12:13]
	s_nop 0
	v_addc_co_u32_e32 v21, vcc, 0, v5, vcc
	s_mov_b32 s12, 0x2a120000
	v_add_co_u32_e32 v12, vcc, s12, v2
	s_mov_b32 s12, 0x2a128000
	s_nop 0
	v_addc_co_u32_e32 v13, vcc, 0, v3, vcc
	v_add_co_u32_e32 v40, vcc, s12, v2
	s_mov_b32 s12, 0x2a130000
	s_nop 0
	v_addc_co_u32_e32 v41, vcc, 0, v3, vcc
	v_add_co_u32_e32 v42, vcc, s12, v2
	s_mov_b32 s12, 0x2a138000
	s_nop 0
	v_addc_co_u32_e32 v43, vcc, 0, v3, vcc
	v_add_co_u32_e32 v44, vcc, s12, v2
	global_load_dwordx4 v[8:11], v[20:21], off
	s_nop 0
	v_addc_co_u32_e32 v45, vcc, 0, v3, vcc
	global_load_dwordx4 v[12:15], v[12:13], off
	s_mov_b64 s[12:13], 0x2b1a0000
	global_load_dwordx4 v[16:19], v[40:41], off
	global_load_dwordx4 v[28:31], v[42:43], off
	global_load_dwordx4 v[32:35], v[44:45], off
	global_load_dwordx4 v[76:79], v[20:21], off offset:64
	global_load_dwordx4 v[80:83], v[6:7], off offset:64
	global_load_dwordx4 v[84:87], v[40:41], off offset:64
	global_load_dwordx4 v[88:91], v[42:43], off offset:64
	global_load_dwordx4 v[92:95], v[44:45], off offset:64
	global_load_dwordx4 v[96:99], v[20:21], off offset:128
	global_load_dwordx4 v[100:103], v[6:7], off offset:128
	global_load_dwordx4 v[104:107], v[40:41], off offset:128
	global_load_dwordx4 v[108:111], v[42:43], off offset:128
	global_load_dwordx4 v[112:115], v[44:45], off offset:128
	global_load_dwordx4 v[116:119], v[20:21], off offset:192
	global_load_dwordx4 v[120:123], v[6:7], off offset:192
	global_load_dwordx4 v[124:127], v[40:41], off offset:192
	global_load_dwordx4 v[128:131], v[42:43], off offset:192
	global_load_dwordx4 v[132:135], v[44:45], off offset:192
	s_waitcnt vmcnt(18)
	v_mfma_f32_16x16x32_bf16 v[12:15], v[12:15], v[8:11], 0
	s_waitcnt vmcnt(17)
	v_mfma_f32_16x16x32_bf16 v[16:19], v[16:19], v[8:11], 0
	s_waitcnt vmcnt(16)
	v_mfma_f32_16x16x32_bf16 v[28:31], v[28:31], v[8:11], 0
	s_waitcnt vmcnt(15)
	v_mfma_f32_16x16x32_bf16 v[8:11], v[32:35], v[8:11], 0
	s_waitcnt vmcnt(0)
; #define LAS __attribute__((address_space(3)))
; __device__ __forceinline__ void skinny_merge(ParamsK p, int l, LAS unsigned char* lds) {
;     ...
; #pragma unroll
;         for (int z = 0; z < 3; ++z) {
;             const bf16_t* A = (const bf16_t*)(p->ws + (z == 0 ? WS_AS5 : (z == 1 ? WS_AGLA : WS_ARET)));
;             const bf16_t* Wt = (const bf16_t*)(p->ws + (z == 0 ? WS_WS5O : (z == 1 ? WS_WGLAO : WS_WRETO)) + l * SZ_WBR);
;             const bf16_t* ap = A + (size_t)(NPROMPT + rh * 64 + r) * 1024 + q * 8 + w * 128;
;             const bf16_t* bp = Wt + (size_t)(cg * 16 + r) * 1024 + q * 8 + w * 128;
;             f32x4 acc[4];
; #pragma unroll
;             for (int mt = 0; mt < 4; ++mt) acc[mt] = (f32x4){0.f, 0.f, 0.f, 0.f};
; #pragma unroll
;             for (int ks = 0; ks < 4; ++ks) {
;                 const bf16x8 b = *(const bf16x8*)(bp + ks * 32);
; #pragma unroll
;                 for (int mt = 0; mt < 4; ++mt) { const bf16x8 a = *(const bf16x8*)(ap + (size_t)mt * 16 * 1024 + ks * 32); acc[mt] = __builtin_amdgcn_mfma_f32_16x16x32_bf16(a, b, acc[mt], 0, 0, 0); }
;             }
; #pragma unroll
;             for (int mt = 0; mt < 4; ++mt) *(LAS f32x4*)(red + (z * 8 + w) * 1024 + (mt * 64 + lane) * 4) = acc[mt];
;         }
;         __syncthreads();
	v_mfma_f32_16x16x32_bf16 v[12:15], v[80:83], v[76:79], v[12:15]
	v_mfma_f32_16x16x32_bf16 v[16:19], v[84:87], v[76:79], v[16:19]
	v_mfma_f32_16x16x32_bf16 v[28:31], v[88:91], v[76:79], v[28:31]
	v_mfma_f32_16x16x32_bf16 v[8:11], v[92:95], v[76:79], v[8:11]
	v_mfma_f32_16x16x32_bf16 v[12:15], v[100:103], v[96:99], v[12:15]
	v_mfma_f32_16x16x32_bf16 v[16:19], v[104:107], v[96:99], v[16:19]
	v_mfma_f32_16x16x32_bf16 v[28:31], v[108:111], v[96:99], v[28:31]
	v_mfma_f32_16x16x32_bf16 v[8:11], v[112:115], v[96:99], v[8:11]
	v_mfma_f32_16x16x32_bf16 v[12:15], v[120:123], v[116:119], v[12:15]
	v_mfma_f32_16x16x32_bf16 v[16:19], v[124:127], v[116:119], v[16:19]
	v_mfma_f32_16x16x32_bf16 v[28:31], v[128:131], v[116:119], v[28:31]
	v_mfma_f32_16x16x32_bf16 v[6:9], v[132:135], v[116:119], v[8:11]
	s_nop 2
	v_lshl_add_u64 v[10:11], v[2:3], 0, s[12:13]
	s_mov_b32 s12, 0x8600000
	v_add_co_u32_e32 v42, vcc, s12, v4
	s_mov_b32 s12, 0x2b1a0000
	s_nop 0
	v_addc_co_u32_e32 v43, vcc, 0, v5, vcc
	ds_write_b128 v47, v[12:15] offset:32768
	ds_write_b128 v47, v[16:19] offset:33792
	ds_write_b128 v47, v[28:31] offset:34816
	ds_write_b128 v47, v[6:9] offset:35840
	v_add_co_u32_e32 v8, vcc, s12, v2
	s_mov_b32 s12, 0x2b1a8000
	s_nop 0
	v_addc_co_u32_e32 v9, vcc, 0, v3, vcc
	v_add_co_u32_e32 v28, vcc, s12, v2
	s_mov_b32 s12, 0x2b1b0000
	s_nop 0
	v_addc_co_u32_e32 v29, vcc, 0, v3, vcc
	v_add_co_u32_e32 v30, vcc, s12, v2
	global_load_dwordx4 v[4:7], v[42:43], off
	s_nop 0
	v_addc_co_u32_e32 v31, vcc, 0, v3, vcc
	global_load_dwordx4 v[32:35], v[30:31], off
	s_mov_b32 s12, 0x2b1b8000
	s_waitcnt vmcnt(0)
	v_mfma_f32_16x16x32_bf16 v[34:37], v[32:35], v[4:7], 0
	v_add_co_u32_e32 v32, vcc, s12, v2
	global_load_dwordx4 v[12:15], v[8:9], off
	global_load_dwordx4 v[16:19], v[28:29], off
	v_addc_co_u32_e32 v33, vcc, 0, v3, vcc
	global_load_dwordx4 v[38:41], v[32:33], off
	s_waitcnt vmcnt(2)
	v_mfma_f32_16x16x32_bf16 v[12:15], v[12:15], v[4:7], 0
	s_waitcnt vmcnt(1)
	v_mfma_f32_16x16x32_bf16 v[16:19], v[16:19], v[4:7], 0
	s_waitcnt vmcnt(0)
	v_mfma_f32_16x16x32_bf16 v[2:5], v[38:41], v[4:7], 0
	global_load_dwordx4 v[6:9], v[42:43], off offset:64
	global_load_dwordx4 v[38:41], v[10:11], off offset:64
	s_waitcnt vmcnt(0)
	v_mfma_f32_16x16x32_bf16 v[12:15], v[38:41], v[6:9], v[12:15]
	global_load_dwordx4 v[38:41], v[28:29], off offset:64
	s_waitcnt vmcnt(0)
	v_mfma_f32_16x16x32_bf16 v[16:19], v[38:41], v[6:9], v[16:19]
	global_load_dwordx4 v[38:41], v[30:31], off offset:64
	s_waitcnt vmcnt(0)
	v_mfma_f32_16x16x32_bf16 v[34:37], v[38:41], v[6:9], v[34:37]
	global_load_dwordx4 v[38:41], v[32:33], off offset:64
	s_waitcnt vmcnt(0)
	v_mfma_f32_16x16x32_bf16 v[2:5], v[38:41], v[6:9], v[2:5]
	global_load_dwordx4 v[6:9], v[42:43], off offset:128
	global_load_dwordx4 v[38:41], v[10:11], off offset:128
	s_waitcnt vmcnt(0)
	v_mfma_f32_16x16x32_bf16 v[38:41], v[38:41], v[6:9], v[12:15]
	s_nop 2
	global_load_dwordx4 v[12:15], v[28:29], off offset:128
	s_waitcnt vmcnt(0)
	v_mfma_f32_16x16x32_bf16 v[18:21], v[12:15], v[6:9], v[16:19]
	global_load_dwordx4 v[12:15], v[30:31], off offset:128
	s_waitcnt vmcnt(0)
	v_mfma_f32_16x16x32_bf16 v[14:17], v[12:15], v[6:9], v[34:37]
	s_nop 2
	global_load_dwordx4 v[34:37], v[32:33], off offset:128
	s_waitcnt vmcnt(0)
	v_mfma_f32_16x16x32_bf16 v[2:5], v[34:37], v[6:9], v[2:5]
	global_load_dwordx4 v[6:9], v[42:43], off offset:192
	s_nop 0
	global_load_dwordx4 v[10:13], v[10:11], off offset:192
	s_nop 0
	global_load_dwordx4 v[34:37], v[28:29], off offset:192
	s_waitcnt vmcnt(1)
	v_mfma_f32_16x16x32_bf16 v[10:13], v[10:13], v[6:9], v[38:41]
	global_load_dwordx4 v[28:31], v[30:31], off offset:192
	s_waitcnt vmcnt(0)
	v_mfma_f32_16x16x32_bf16 v[14:17], v[28:31], v[6:9], v[14:17]
	global_load_dwordx4 v[28:31], v[32:33], off offset:192
	v_mfma_f32_16x16x32_bf16 v[18:21], v[34:37], v[6:9], v[18:21]
	s_waitcnt vmcnt(0)
	v_mfma_f32_16x16x32_bf16 v[2:5], v[28:31], v[6:9], v[2:5]
	s_nop 0
	ds_write_b128 v49, v[10:13]
	s_nop 3
	ds_write_b128 v50, v[18:21]
	ds_write_b128 v51, v[14:17]
	ds_write_b128 v52, v[2:5]
	s_waitcnt lgkmcnt(0)
	s_barrier
; __device__ __forceinline__ bf16_t f2bf(float f) { return (bf16_t)(cvt_pk_bf16(f, 0.f) & 0xffffu); }
; __device__ __forceinline__ float bf2f(bf16_t b) { return __uint_as_float(((unsigned)b) << 16); }
; __device__ __forceinline__ void skinny_merge(ParamsK p, int l, LAS unsigned char* lds) {
;     ...
; #pragma unroll
;         for (int h = 0; h < 2; ++h) {
;             const int e = tid + h * 512;
;             const int mt = e >> 8, ln = (e >> 2) & 63, j = e & 3;
;             const int row = NPROMPT + rh * 64 + mt * 16 + (ln >> 4) * 4 + j, col = cg * 16 + (ln & 15);
;             float tot = 0.f;
; #pragma unroll
;             for (int z = 0; z < 3; ++z) { float sum = 0.f;
; #pragma unroll
;                 for (int ww = 0; ww < 8; ++ww) sum += red[(z * 8 + ww) * 1024 + e];
;                 tot += sum * bf2f(proj[(size_t)row * NIN + OFF_MG + z * 2048 + col]); }
;             O[(size_t)row * DM + col] = f2bf(tot);
;         }
;         __syncthreads();
	ds_read2st64_b32 v[8:9], v55 offset1:8
	v_or_b32_e32 v2, s11, v48
	ds_read2st64_b32 v[10:11], v55 offset0:16 offset1:24
	v_ashrrev_i32_e32 v3, 31, v2
	v_lshlrev_b64 v[2:3], 1, v[2:3]
	v_lshl_add_u64 v[6:7], s[6:7], 0, v[2:3]
	v_add_u32_e32 v4, v0, v54
	v_mad_i64_i32 v[74:75], s[10:11], v4, s73, v[6:7]
	s_waitcnt lgkmcnt(1)
	v_add_f32_e32 v8, 0, v8
	s_waitcnt lgkmcnt(0)
	v_add_f32_e32 v8, v8, v10
	global_load_ushort v10, v[74:75], off
	ds_read2st64_b32 v[12:13], v55 offset0:32 offset1:40
	v_add_co_u32_e32 v74, vcc, s39, v74
	ds_read2st64_b32 v[14:15], v55 offset0:48 offset1:56
	s_nop 0
	v_addc_co_u32_e32 v75, vcc, 0, v75, vcc
	s_waitcnt lgkmcnt(1)
	v_add_f32_e32 v8, v8, v12
	global_load_ushort v12, v[74:75], off offset:-4096
	ds_read2st64_b32 v[16:17], v55 offset0:64 offset1:72
	ds_read2st64_b32 v[18:19], v55 offset0:80 offset1:88
	ds_read2st64_b32 v[20:21], v55 offset0:96 offset1:104
	ds_read2st64_b32 v[28:29], v55 offset0:112 offset1:120
	s_waitcnt lgkmcnt(4)
	v_add_f32_e32 v8, v8, v14
	ds_read2st64_b32 v[30:31], v55 offset0:128 offset1:136
	s_waitcnt lgkmcnt(4)
	v_add_f32_e32 v8, v8, v16
	ds_read2st64_b32 v[32:33], v55 offset0:144 offset1:152
	s_waitcnt lgkmcnt(4)
	v_add_f32_e32 v8, v8, v18
	ds_read2st64_b32 v[34:35], v55 offset0:160 offset1:168
	s_waitcnt lgkmcnt(4)
	v_add_f32_e32 v8, v8, v20
	ds_read2st64_b32 v[36:37], v55 offset0:176 offset1:184
	s_waitcnt lgkmcnt(4)
	v_add_f32_e32 v8, v8, v28
	ds_read2st64_b32 v[38:39], v55 offset0:192 offset1:200
	ds_read2st64_b32 v[40:41], v55 offset0:208 offset1:216
	ds_read2st64_b32 v[42:43], v55 offset0:224 offset1:232
	ds_read2st64_b32 v[44:45], v55 offset0:240 offset1:248
	v_ashrrev_i32_e32 v5, 31, v4
	v_lshl_add_u64 v[2:3], s[4:5], 0, v[2:3]
	v_lshlrev_b64 v[4:5], 12, v[4:5]
	v_lshl_add_u64 v[4:5], v[2:3], 0, v[4:5]
	s_waitcnt vmcnt(1)
	v_lshlrev_b32_e32 v10, 16, v10
	v_fma_f32 v8, v8, v10, 0
	s_waitcnt lgkmcnt(7)
	v_add_f32_e32 v10, 0, v30
	s_waitcnt lgkmcnt(6)
	v_add_f32_e32 v10, v10, v32
	s_waitcnt lgkmcnt(5)
	v_add_f32_e32 v10, v10, v34
	s_waitcnt lgkmcnt(4)
	v_add_f32_e32 v10, v10, v36
	s_waitcnt lgkmcnt(3)
	v_add_f32_e32 v10, v10, v38
	s_waitcnt lgkmcnt(2)
	v_add_f32_e32 v10, v10, v40
	s_waitcnt lgkmcnt(1)
	v_add_f32_e32 v10, v10, v42
	s_waitcnt lgkmcnt(0)
	v_add_f32_e32 v10, v10, v44
	s_waitcnt vmcnt(0)
	v_lshlrev_b32_e32 v12, 16, v12
	v_fmac_f32_e32 v8, v10, v12
	ds_read_b32 v10, v56
	ds_read_b32 v12, v57
	s_waitcnt lgkmcnt(1)
	v_add_f32_e32 v10, 0, v10
	s_waitcnt lgkmcnt(0)
	v_add_f32_e32 v10, v10, v12
	ds_read_b32 v12, v58
	s_waitcnt lgkmcnt(0)
	v_add_f32_e32 v10, v10, v12
	ds_read_b32 v12, v59
	s_waitcnt lgkmcnt(0)
	v_add_f32_e32 v10, v10, v12
	ds_read_b32 v12, v60
	s_waitcnt lgkmcnt(0)
	v_add_f32_e32 v10, v10, v12
	ds_read_b32 v12, v61
	s_waitcnt lgkmcnt(0)
	v_add_f32_e32 v10, v10, v12
	ds_read_b32 v12, v62
	s_waitcnt lgkmcnt(0)
	v_add_f32_e32 v10, v10, v12
	ds_read_b32 v12, v63
	s_waitcnt lgkmcnt(0)
	v_add_f32_e32 v10, v10, v12
	global_load_ushort v12, v[74:75], off
	s_waitcnt vmcnt(0)
	v_lshlrev_b32_e32 v12, 16, v12
	v_fmac_f32_e32 v8, v10, v12
	v_cvt_pk_bf16_f32 v8, v8, s0
	global_store_short v[4:5], v8, off
	v_add_u32_e32 v4, v0, v64
	v_mad_i64_i32 v[6:7], s[10:11], v4, s73, v[6:7]
	global_load_ushort v8, v[6:7], off
	v_add_co_u32_e32 v6, vcc, s39, v6
	v_add_f32_e32 v0, 0, v9
	s_nop 0
	v_addc_co_u32_e32 v7, vcc, 0, v7, vcc
	global_load_ushort v9, v[6:7], off offset:-4096
	v_add_f32_e32 v0, v0, v11
	global_load_ushort v6, v[6:7], off
	v_add_f32_e32 v0, v0, v13
	v_add_f32_e32 v0, v0, v15
	v_add_f32_e32 v0, v0, v17
	v_add_f32_e32 v0, v0, v19
	v_add_f32_e32 v0, v0, v21
	v_add_f32_e32 v0, v0, v29
	v_ashrrev_i32_e32 v5, 31, v4
	v_lshlrev_b64 v[4:5], 12, v[4:5]
	v_lshl_add_u64 v[2:3], v[2:3], 0, v[4:5]
	s_waitcnt vmcnt(2)
	v_lshlrev_b32_e32 v8, 16, v8
	v_fma_f32 v0, v0, v8, 0
	v_add_f32_e32 v8, 0, v31
	v_add_f32_e32 v8, v8, v33
	v_add_f32_e32 v8, v8, v35
	v_add_f32_e32 v8, v8, v37
	v_add_f32_e32 v8, v8, v39
	v_add_f32_e32 v8, v8, v41
	v_add_f32_e32 v8, v8, v43
	v_add_f32_e32 v8, v8, v45
	s_waitcnt vmcnt(1)
	v_lshlrev_b32_e32 v9, 16, v9
	v_fmac_f32_e32 v0, v8, v9
	ds_read_b32 v8, v65
	ds_read_b32 v9, v66
	s_waitcnt vmcnt(0)
	v_lshlrev_b32_e32 v6, 16, v6
	s_waitcnt lgkmcnt(1)
	v_add_f32_e32 v8, 0, v8
	s_waitcnt lgkmcnt(0)
	v_add_f32_e32 v8, v8, v9
	ds_read_b32 v9, v67
	s_waitcnt lgkmcnt(0)
	v_add_f32_e32 v8, v8, v9
	ds_read_b32 v9, v68
	s_waitcnt lgkmcnt(0)
	v_add_f32_e32 v8, v8, v9
	ds_read_b32 v9, v69
	s_waitcnt lgkmcnt(0)
	v_add_f32_e32 v8, v8, v9
	ds_read_b32 v9, v70
	s_waitcnt lgkmcnt(0)
	v_add_f32_e32 v8, v8, v9
	ds_read_b32 v9, v71
	s_waitcnt lgkmcnt(0)
	v_add_f32_e32 v8, v8, v9
	ds_read_b32 v9, v72
	s_waitcnt lgkmcnt(0)
	v_add_f32_e32 v8, v8, v9
	v_fmac_f32_e32 v0, v8, v6
	v_cvt_pk_bf16_f32 v0, v0, s0
	global_store_short v[2:3], v0, off
	s_barrier
	s_cbranch_scc1 .LBB0_1271
